# weight prep rebalanced: layer-1 FFN1 down weights converted in phase 11 instead of 9, last FFN down weights in phase 19
# baseline (speedup 1.0000x reference)
.LBB0_923:
	s_and_b64 vcc, exec, s[6:7]
	s_cbranch_vccz .LBB0_1018
	s_cmpk_lt_i32 s31, 0x80
	s_cbranch_scc1 .LBB0_1018
	s_lshl_b32 s0, s31, 3
	s_add_i32 s4, s0, 0xfffffc00
	v_add_u32_e32 v43, s4, v5
	s_and_b64 s[6:7], s[12:13], exec
	s_movk_i32 s4, 0x2100
	s_cselect_b32 s4, s4, 0x3180
	s_and_b64 s[6:7], s[16:17], exec
	s_cselect_b32 s28, 0xb00, s4
	s_and_b64 s[6:7], s[12:13], exec
	s_movk_i32 s4, 0x4200
	s_cselect_b32 s4, 0x3180, s4
	s_and_b64 s[6:7], s[16:17], exec
	s_cselect_b32 s8, 0x2100, s4
	s_and_b64 s[6:7], s[12:13], exec
	s_cselect_b32 s4, 0x4800, 0
	s_and_b64 s[6:7], s[16:17], exec
	s_cselect_b32 s4, 0x4200, s4
	s_and_b64 s[6:7], s[12:13], exec
	s_cselect_b32 s9, 0x5000, 0
	s_and_b64 s[6:7], s[16:17], exec
	s_cselect_b32 s6, 0x4800, s9
	s_cmp_eq_u32 s86, 11
	s_cbranch_scc0 .Lp19a
	s_movk_i32 s8, 0x3c80
	s_movk_i32 s28, 0x2c00
.Lp19a:
	s_cmp_eq_u32 s86, 9
	s_cbranch_scc0 .Lp19c
	s_movk_i32 s8, 0x2c00
